# SGU group: bias and u loads issued before the group MFMAs instead of after (latency hidden behind matrix work)
# baseline (speedup 1.0000x reference)
; #define LAS __attribute__((address_space(3)))
; __device__ __forceinline__ unsigned cvt_pk_bf16(float lo, float hi) { f32x2 v = {lo, hi}; bf16x2_t b = __builtin_convertvector(v, bf16x2_t); return __builtin_bit_cast(unsigned, b); }
; __device__ __forceinline__ float bf_lo(unsigned w) { return __uint_as_float(w << 16); }
; __device__ __forceinline__ float bf_hi(unsigned w) { return __uint_as_float(w & 0xffff0000u); }
; __device__ __forceinline__ void sgu_chunk(const Ctx& C, const Args& a, int l, int n) {
;     ...
;     for (int g = 0; g < 8; ++g) {
; #pragma unroll
;         for (int j = 0; j < 4; ++j) { const int p = C.tid + 512 * j, r = p >> 4, c8 = (p & 15) * 8; const f32x2 st = stats[r];
;             const u32x4 w = *(const u32x4*)(VB + (R0 + r) * D + g * 128 + c8); const f32x4 g0 = *(const f32x4*)(gam + g * 128 + c8), g1 = *(const f32x4*)(gam + g * 128 + c8 + 4);
;             const f32x4 b0 = *(const f32x4*)(bet + g * 128 + c8), b1 = *(const f32x4*)(bet + g * 128 + c8 + 4);
;             u32x4 o; o.x = cvt_pk_bf16((bf_lo(w.x) - st.x) * st.y * g0[0] + b0[0], (bf_hi(w.x) - st.x) * st.y * g0[1] + b0[1]);
;             o.y = cvt_pk_bf16((bf_lo(w.y) - st.x) * st.y * g0[2] + b0[2], (bf_hi(w.y) - st.x) * st.y * g0[3] + b0[3]);
;             o.z = cvt_pk_bf16((bf_lo(w.z) - st.x) * st.y * g1[0] + b1[0], (bf_hi(w.z) - st.x) * st.y * g1[1] + b1[1]);
;             o.w = cvt_pk_bf16((bf_lo(w.w) - st.x) * st.y * g1[2] + b1[2], (bf_hi(w.w) - st.x) * st.y * g1[3] + b1[3]);
;             *(LAS u32x4*)(vimg + (c8 >> 5) * 8192 + r * 64 + (c8 & 31) * 2) = o; }
.LBB0_154:
	v_lshl_add_u64 v[78:79], s[86:87], 0, v[56:57]
	global_load_dwordx2 v[206:207], v[78:79], off offset:-128
	global_load_dwordx2 v[208:209], v[78:79], off offset:-112
	global_load_dwordx2 v[210:211], v[78:79], off offset:-96
	global_load_dwordx2 v[212:213], v[78:79], off offset:-80
	global_load_dwordx2 v[214:215], v[78:79], off offset:-64
	global_load_dwordx2 v[216:217], v[78:79], off offset:-48
	global_load_dwordx2 v[218:219], v[78:79], off offset:-32
	global_load_dwordx2 v[220:221], v[78:79], off offset:-16
	global_load_dwordx2 v[232:233], v[78:79], off offset:0
	global_load_dwordx2 v[234:235], v[78:79], off offset:16
	global_load_dwordx2 v[236:237], v[78:79], off offset:32
	global_load_dwordx2 v[238:239], v[78:79], off offset:48
	global_load_dwordx2 v[240:241], v[78:79], off offset:64
	global_load_dwordx2 v[242:243], v[78:79], off offset:80
	global_load_dwordx2 v[244:245], v[78:79], off offset:96
	global_load_dwordx2 v[246:247], v[78:79], off offset:112
	v_lshl_add_u64 v[176:177], s[86:87], 0, v[62:63]
	global_load_dwordx4 v[164:167], v[176:177], off
	v_lshl_add_u64 v[176:177], s[86:87], 0, v[60:61]
	global_load_dwordx4 v[168:171], v[176:177], off
	v_lshl_add_u64 v[176:177], s[86:87], 0, v[58:59]
	global_load_dwordx4 v[172:175], v[176:177], off
	v_lshl_add_u64 v[0:1], s[86:87], 0, v[64:65]
	global_load_dwordx4 v[16:19], v[0:1], off
	v_lshl_add_u64 v[0:1], v[52:53], 0, s[44:45]
	v_lshl_add_u64 v[8:9], v[54:55], 0, s[44:45]
	ds_read_b64 v[20:21], v68
	global_load_dwordx4 v[4:7], v[0:1], off offset:-16
	s_nop 0
	global_load_dwordx4 v[0:3], v[0:1], off
	s_nop 0
	global_load_dwordx4 v[12:15], v[8:9], off offset:-16
	s_nop 0
	global_load_dwordx4 v[8:11], v[8:9], off
	s_add_u32 s18, s24, s44
	s_addc_u32 s19, s25, s45
	s_mov_b32 s12, 0x5c00000
	v_lshl_add_u64 v[64:65], v[64:65], 0, s[14:15]
	v_lshl_add_u64 v[56:57], v[56:57], 0, s[94:95]
	s_waitcnt vmcnt(4)
	v_lshlrev_b32_e32 v22, 16, v16
	v_and_b32_e32 v23, 0xffff0000, v16
	s_waitcnt lgkmcnt(0)
	v_pk_add_f32 v[22:23], v[22:23], v[20:21] op_sel_hi:[1,0] neg_lo:[0,1] neg_hi:[0,1]
	s_nop 0
	v_pk_mul_f32 v[22:23], v[20:21], v[22:23] op_sel:[1,0]
	s_waitcnt vmcnt(1)
	v_pk_fma_f32 v[22:23], v[4:5], v[22:23], v[12:13]
	s_nop 0
	v_cvt_pk_bf16_f32 v16, v22, v23
	v_lshlrev_b32_e32 v22, 16, v17
	v_and_b32_e32 v23, 0xffff0000, v17
	v_pk_add_f32 v[22:23], v[22:23], v[20:21] op_sel_hi:[1,0] neg_lo:[0,1] neg_hi:[0,1]
	s_nop 0
	v_pk_mul_f32 v[22:23], v[20:21], v[22:23] op_sel:[1,0]
	s_nop 0
	v_pk_fma_f32 v[22:23], v[6:7], v[22:23], v[14:15]
	s_nop 0
	v_cvt_pk_bf16_f32 v17, v22, v23
	v_lshlrev_b32_e32 v22, 16, v18
	v_and_b32_e32 v23, 0xffff0000, v18
	v_pk_add_f32 v[22:23], v[22:23], v[20:21] op_sel_hi:[1,0] neg_lo:[0,1] neg_hi:[0,1]
	s_nop 0
	v_pk_mul_f32 v[22:23], v[20:21], v[22:23] op_sel:[1,0]
	s_waitcnt vmcnt(0)
	v_pk_fma_f32 v[22:23], v[0:1], v[22:23], v[8:9]
	s_nop 0
	v_cvt_pk_bf16_f32 v18, v22, v23
	v_lshlrev_b32_e32 v22, 16, v19
	v_and_b32_e32 v23, 0xffff0000, v19
	v_pk_add_f32 v[22:23], v[22:23], v[20:21] op_sel_hi:[1,0] neg_lo:[0,1] neg_hi:[0,1]
	s_nop 0
	v_pk_mul_f32 v[20:21], v[20:21], v[22:23] op_sel:[1,0]
	s_nop 0
	v_pk_fma_f32 v[20:21], v[2:3], v[20:21], v[10:11]
	s_nop 0
	v_cvt_pk_bf16_f32 v19, v20, v21
	ds_write_b128 v72, v[16:19] offset:1024
	v_mov_b32_e32 v16, v164
	v_mov_b32_e32 v17, v165
	v_mov_b32_e32 v18, v166
	v_mov_b32_e32 v19, v167
	ds_read_b64 v[20:21], v69
	v_lshl_add_u64 v[62:63], v[62:63], 0, s[14:15]
	s_waitcnt vmcnt(0)
	v_lshlrev_b32_e32 v22, 16, v16
	v_and_b32_e32 v23, 0xffff0000, v16
	s_waitcnt lgkmcnt(0)
	v_pk_add_f32 v[22:23], v[22:23], v[20:21] op_sel_hi:[1,0] neg_lo:[0,1] neg_hi:[0,1]
	s_nop 0
	v_pk_mul_f32 v[22:23], v[20:21], v[22:23] op_sel:[1,0]
	s_nop 0
	v_pk_fma_f32 v[22:23], v[4:5], v[22:23], v[12:13]
	s_nop 0
	v_cvt_pk_bf16_f32 v16, v22, v23
	v_lshlrev_b32_e32 v22, 16, v17
	v_and_b32_e32 v23, 0xffff0000, v17
	v_pk_add_f32 v[22:23], v[22:23], v[20:21] op_sel_hi:[1,0] neg_lo:[0,1] neg_hi:[0,1]
	s_nop 0
	v_pk_mul_f32 v[22:23], v[20:21], v[22:23] op_sel:[1,0]
	s_nop 0
	v_pk_fma_f32 v[22:23], v[6:7], v[22:23], v[14:15]
	s_nop 0
	v_cvt_pk_bf16_f32 v17, v22, v23
	v_lshlrev_b32_e32 v22, 16, v18
	v_and_b32_e32 v23, 0xffff0000, v18
	v_pk_add_f32 v[22:23], v[22:23], v[20:21] op_sel_hi:[1,0] neg_lo:[0,1] neg_hi:[0,1]
	s_nop 0
	v_pk_mul_f32 v[22:23], v[20:21], v[22:23] op_sel:[1,0]
	s_nop 0
	v_pk_fma_f32 v[22:23], v[0:1], v[22:23], v[8:9]
	s_nop 0
	v_cvt_pk_bf16_f32 v18, v22, v23
	v_lshlrev_b32_e32 v22, 16, v19
	v_and_b32_e32 v23, 0xffff0000, v19
	v_pk_add_f32 v[22:23], v[22:23], v[20:21] op_sel_hi:[1,0] neg_lo:[0,1] neg_hi:[0,1]
	s_nop 0
	v_pk_mul_f32 v[20:21], v[20:21], v[22:23] op_sel:[1,0]
	s_nop 0
	v_pk_fma_f32 v[20:21], v[2:3], v[20:21], v[10:11]
	s_nop 0
	v_cvt_pk_bf16_f32 v19, v20, v21
	ds_write_b128 v73, v[16:19] offset:1024
	v_mov_b32_e32 v16, v168
	v_mov_b32_e32 v17, v169
	v_mov_b32_e32 v18, v170
	v_mov_b32_e32 v19, v171
	ds_read_b64 v[20:21], v70
	v_lshl_add_u64 v[60:61], v[60:61], 0, s[14:15]
	s_waitcnt vmcnt(0)
	v_lshlrev_b32_e32 v22, 16, v16
	v_and_b32_e32 v23, 0xffff0000, v16
	s_waitcnt lgkmcnt(0)
; __device__ __forceinline__ void sgu_chunk(const Ctx& C, const Args& a, int l, int n) {
;     ...
;         for (int j = 0; j < 4; ++j) { const int p = C.tid + 512 * j, r = p >> 4, c8 = (p & 15) * 8; const f32x2 st = stats[r];
;             const u32x4 w = *(const u32x4*)(VB + (R0 + r) * D + g * 128 + c8); const f32x4 g0 = *(const f32x4*)(gam + g * 128 + c8), g1 = *(const f32x4*)(gam + g * 128 + c8 + 4);
;             const f32x4 b0 = *(const f32x4*)(bet + g * 128 + c8), b1 = *(const f32x4*)(bet + g * 128 + c8 + 4);
;             u32x4 o; o.x = cvt_pk_bf16((bf_lo(w.x) - st.x) * st.y * g0[0] + b0[0], (bf_hi(w.x) - st.x) * st.y * g0[1] + b0[1]);
;             o.y = cvt_pk_bf16((bf_lo(w.y) - st.x) * st.y * g0[2] + b0[2], (bf_hi(w.y) - st.x) * st.y * g0[3] + b0[3]);
;             o.z = cvt_pk_bf16((bf_lo(w.z) - st.x) * st.y * g1[0] + b1[0], (bf_hi(w.z) - st.x) * st.y * g1[1] + b1[1]);
;             o.w = cvt_pk_bf16((bf_lo(w.w) - st.x) * st.y * g1[2] + b1[2], (bf_hi(w.w) - st.x) * st.y * g1[3] + b1[3]);
;             *(LAS u32x4*)(vimg + (c8 >> 5) * 8192 + r * 64 + (c8 & 31) * 2) = o; }
;         __syncthreads();
;         f32x16 acc[2];
; #pragma unroll
;         for (int r = 0; r < 16; ++r) { acc[0][r] = 0.f; acc[1][r] = 0.f; }
;         const bf16_t* wrow = SW + ((size_t)g * 128 + 32 * tb + r32) * 128 + 4 * hi;
; #pragma unroll
;         for (int kc = 0; kc < 8; ++kc) {
;             const u32x2 alo = *(const u32x2*)(wrow + 16 * kc), ahi = *(const u32x2*)(wrow + 16 * kc + 8);
;             const bf16x8 af = __builtin_bit_cast(bf16x8, (u32x4){alo.x, alo.y, ahi.x, ahi.y});
; #pragma unroll
;             for (int j = 0; j < 2; ++j) { LAS const unsigned char* vp = vimg + (2 * ch + j) * 8192 + kc * 1024 + voff; const s16x4 lo = att::vtr(vp), hh = att::vtr(vp + 512);
;                 const bf16x8 vf = (bf16x8){lo[0], lo[1], lo[2], lo[3], hh[0], hh[1], hh[2], hh[3]}; acc[j] = ATT_MFMA(af, vf, acc[j]); }
;         }
;         int hi_e = hi, r32_e = r32; asm volatile("" : "+v"(hi_e), "+v"(r32_e));
;         const float* sbp = sb + g * 128 + 32 * tb + 4 * hi_e; bf16_t* hp = HC + (R0 + 32 * tb + 4 * hi_e) * 2048 + g * 128 + 64 * ch + r32_e;
;         bf16_t uu[16][2]; float bsv[16];
; #pragma unroll
;         for (int r = 0; r < 16; ++r) { bsv[r] = sbp[att::crow(r, 0)];
; #pragma unroll
;             for (int j = 0; j < 2; ++j) uu[r][j] = hp[att::crow(r, 0) * 2048 + 32 * j]; }
	v_pk_add_f32 v[22:23], v[22:23], v[20:21] op_sel_hi:[1,0] neg_lo:[0,1] neg_hi:[0,1]
	s_nop 0
	v_pk_mul_f32 v[22:23], v[20:21], v[22:23] op_sel:[1,0]
	s_nop 0
	v_pk_fma_f32 v[22:23], v[4:5], v[22:23], v[12:13]
	s_nop 0
	v_cvt_pk_bf16_f32 v16, v22, v23
	v_lshlrev_b32_e32 v22, 16, v17
	v_and_b32_e32 v23, 0xffff0000, v17
	v_pk_add_f32 v[22:23], v[22:23], v[20:21] op_sel_hi:[1,0] neg_lo:[0,1] neg_hi:[0,1]
	s_nop 0
	v_pk_mul_f32 v[22:23], v[20:21], v[22:23] op_sel:[1,0]
	s_nop 0
	v_pk_fma_f32 v[22:23], v[6:7], v[22:23], v[14:15]
	s_nop 0
	v_cvt_pk_bf16_f32 v17, v22, v23
	v_lshlrev_b32_e32 v22, 16, v18
	v_and_b32_e32 v23, 0xffff0000, v18
	v_pk_add_f32 v[22:23], v[22:23], v[20:21] op_sel_hi:[1,0] neg_lo:[0,1] neg_hi:[0,1]
	s_nop 0
	v_pk_mul_f32 v[22:23], v[20:21], v[22:23] op_sel:[1,0]
	s_nop 0
	v_pk_fma_f32 v[22:23], v[0:1], v[22:23], v[8:9]
	s_nop 0
	v_cvt_pk_bf16_f32 v18, v22, v23
	v_lshlrev_b32_e32 v22, 16, v19
	v_and_b32_e32 v23, 0xffff0000, v19
	v_pk_add_f32 v[22:23], v[22:23], v[20:21] op_sel_hi:[1,0] neg_lo:[0,1] neg_hi:[0,1]
	s_nop 0
	v_pk_mul_f32 v[20:21], v[20:21], v[22:23] op_sel:[1,0]
	s_nop 0
	v_pk_fma_f32 v[20:21], v[2:3], v[20:21], v[10:11]
	s_nop 0
	v_cvt_pk_bf16_f32 v19, v20, v21
	ds_write_b128 v74, v[16:19] offset:1024
	v_mov_b32_e32 v16, v172
	v_mov_b32_e32 v17, v173
	v_mov_b32_e32 v18, v174
	v_mov_b32_e32 v19, v175
	ds_read_b64 v[20:21], v71
	v_lshl_add_u64 v[58:59], v[58:59], 0, s[14:15]
	s_waitcnt vmcnt(0)
	v_lshlrev_b32_e32 v22, 16, v16
	v_and_b32_e32 v23, 0xffff0000, v16
	s_waitcnt lgkmcnt(0)
	v_pk_add_f32 v[22:23], v[22:23], v[20:21] op_sel_hi:[1,0] neg_lo:[0,1] neg_hi:[0,1]
	s_nop 0
	v_pk_mul_f32 v[22:23], v[20:21], v[22:23] op_sel:[1,0]
	s_nop 0
	v_pk_fma_f32 v[4:5], v[4:5], v[22:23], v[12:13]
	v_lshlrev_b32_e32 v12, 16, v17
	v_and_b32_e32 v13, 0xffff0000, v17
	v_pk_add_f32 v[12:13], v[12:13], v[20:21] op_sel_hi:[1,0] neg_lo:[0,1] neg_hi:[0,1]
	v_cvt_pk_bf16_f32 v4, v4, v5
	v_pk_mul_f32 v[12:13], v[20:21], v[12:13] op_sel:[1,0]
	s_nop 0
	v_pk_fma_f32 v[6:7], v[6:7], v[12:13], v[14:15]
	s_nop 0
	v_cvt_pk_bf16_f32 v5, v6, v7
	v_lshlrev_b32_e32 v6, 16, v18
	v_and_b32_e32 v7, 0xffff0000, v18
	v_pk_add_f32 v[6:7], v[6:7], v[20:21] op_sel_hi:[1,0] neg_lo:[0,1] neg_hi:[0,1]
	s_nop 0
	v_pk_mul_f32 v[6:7], v[20:21], v[6:7] op_sel:[1,0]
	s_nop 0
	v_pk_fma_f32 v[0:1], v[0:1], v[6:7], v[8:9]
	s_nop 0
	v_cvt_pk_bf16_f32 v6, v0, v1
	v_lshlrev_b32_e32 v0, 16, v19
	v_and_b32_e32 v1, 0xffff0000, v19
	v_pk_add_f32 v[0:1], v[0:1], v[20:21] op_sel_hi:[1,0] neg_lo:[0,1] neg_hi:[0,1]
	s_nop 0
	v_pk_mul_f32 v[0:1], v[20:21], v[0:1] op_sel:[1,0]
	s_nop 0
	v_pk_fma_f32 v[0:1], v[2:3], v[0:1], v[10:11]
	s_nop 0
	v_cvt_pk_bf16_f32 v7, v0, v1
	ds_write_b128 v75, v[4:7] offset:1024
	s_waitcnt lgkmcnt(0)
	s_barrier
	ds_read_b64_tr_b16 v[4:5], v76 offset:1024
	ds_read_b64_tr_b16 v[6:7], v76 offset:1536
	v_mov_b32_e32 v32, v66
	v_mov_b32_e32 v33, v67
	s_nop 0
	v_lshlrev_b32_e32 v34, 2, v33
	v_ashrrev_i32_e32 v35, 31, v34
	v_lshl_add_u64 v[86:87], v[34:35], 2, s[18:19]
	v_lshl_add_u64 v[34:35], s[40:41], 0, v[34:35]
	v_ashrrev_i32_e32 v33, 31, v32
	v_lshlrev_b64 v[34:35], 12, v[34:35]
	s_add_u32 s18, s86, s46
	v_lshl_add_u64 v[32:33], v[32:33], 1, v[34:35]
	s_addc_u32 s19, s87, s47
	v_lshl_add_u64 v[88:89], s[18:19], 0, v[32:33]
	global_load_dwordx4 v[78:81], v[86:87], off
	global_load_dwordx4 v[82:85], v[86:87], off offset:32
	global_load_dwordx4 v[164:167], v[86:87], off offset:64
	global_load_dwordx4 v[32:35], v[86:87], off offset:96
	v_lshrrev_b32_e32 v90, 1, v230
	v_lshlrev_b32_e32 v91, 2, v67
	v_sub_u32_e32 v90, v90, v91
	v_lshlrev_b32_e32 v90, 12, v90
	v_and_b32_e32 v91, 1, v230
	v_lshl_add_u32 v90, v91, 6, v90
	v_lshlrev_b32_e32 v91, 1, v66
	v_sub_u32_e32 v90, v90, v91
	v_add_u32_e32 v90, 0x5c00000, v90
	v_mov_b32_e32 v91, 0
	v_lshl_add_u64 v[92:93], v[88:89], 0, v[90:91]
	global_load_dwordx4 v[128:131], v[92:93], off
	global_load_dwordx4 v[132:135], v[92:93], off offset:16
	global_load_dwordx4 v[136:139], v[92:93], off offset:32
	global_load_dwordx4 v[140:143], v[92:93], off offset:48
	s_waitcnt lgkmcnt(0)
	v_mfma_f32_32x32x16_bf16 v[16:31], v[206:209], v[4:7], 0
	ds_read_b64_tr_b16 v[4:5], v76 offset:9216
	ds_read_b64_tr_b16 v[6:7], v76 offset:9728
	ds_read_b64_tr_b16 v[36:37], v76 offset:2048
	ds_read_b64_tr_b16 v[38:39], v76 offset:2560
	s_waitcnt lgkmcnt(2)
	v_mfma_f32_32x32x16_bf16 v[0:15], v[206:209], v[4:7], 0
	s_waitcnt lgkmcnt(0)
	v_mfma_f32_32x32x16_bf16 v[16:31], v[210:213], v[36:39], v[16:31]
	ds_read_b64_tr_b16 v[36:37], v76 offset:10240
	ds_read_b64_tr_b16 v[38:39], v76 offset:10752
	s_waitcnt lgkmcnt(0)
	v_mfma_f32_32x32x16_bf16 v[0:15], v[210:213], v[36:39], v[0:15]
	ds_read_b64_tr_b16 v[36:37], v76 offset:3072
	ds_read_b64_tr_b16 v[38:39], v76 offset:3584
	s_waitcnt lgkmcnt(0)
	v_mfma_f32_32x32x16_bf16 v[16:31], v[214:217], v[36:39], v[16:31]
	ds_read_b64_tr_b16 v[36:37], v76 offset:11264
	ds_read_b64_tr_b16 v[38:39], v76 offset:11776
	s_waitcnt lgkmcnt(0)
	v_mfma_f32_32x32x16_bf16 v[0:15], v[214:217], v[36:39], v[0:15]
	ds_read_b64_tr_b16 v[36:37], v76 offset:4096
	ds_read_b64_tr_b16 v[38:39], v76 offset:4608
	s_waitcnt lgkmcnt(0)
	v_mfma_f32_32x32x16_bf16 v[16:31], v[218:221], v[36:39], v[16:31]
	ds_read_b64_tr_b16 v[36:37], v76 offset:12288
	ds_read_b64_tr_b16 v[38:39], v76 offset:12800
	s_waitcnt lgkmcnt(0)
	v_mfma_f32_32x32x16_bf16 v[0:15], v[218:221], v[36:39], v[0:15]
	ds_read_b64_tr_b16 v[36:37], v76 offset:5120
	ds_read_b64_tr_b16 v[38:39], v76 offset:5632
	s_waitcnt lgkmcnt(0)
	v_mfma_f32_32x32x16_bf16 v[16:31], v[232:235], v[36:39], v[16:31]
	ds_read_b64_tr_b16 v[36:37], v76 offset:13312
	ds_read_b64_tr_b16 v[38:39], v76 offset:13824
	s_waitcnt lgkmcnt(0)
; #define LAS __attribute__((address_space(3)))
; __device__ __forceinline__ unsigned cvt_pk_bf16(float lo, float hi) { f32x2 v = {lo, hi}; bf16x2_t b = __builtin_convertvector(v, bf16x2_t); return __builtin_bit_cast(unsigned, b); }
; __device__ __forceinline__ int crow(int r, int hi) { return (r & 3) + 8 * (r >> 2) + 4 * hi; }
; __device__ __forceinline__ s16x4 vtr(LAS const unsigned char* p) { return __builtin_bit_cast(s16x4, __builtin_amdgcn_ds_read_tr16_b64_v4i16((LAS v4i16_t*)p)); }
; #define ATT_MFMA(a, b, c) __builtin_amdgcn_mfma_f32_32x32x16_bf16(a, b, c, 0, 0, 0)
; __device__ __forceinline__ void sgu_chunk(const Ctx& C, const Args& a, int l, int n) {
;     ...
;         for (int kc = 0; kc < 8; ++kc) {
;             const u32x2 alo = *(const u32x2*)(wrow + 16 * kc), ahi = *(const u32x2*)(wrow + 16 * kc + 8);
;             const bf16x8 af = __builtin_bit_cast(bf16x8, (u32x4){alo.x, alo.y, ahi.x, ahi.y});
; #pragma unroll
;             for (int j = 0; j < 2; ++j) { LAS const unsigned char* vp = vimg + (2 * ch + j) * 8192 + kc * 1024 + voff; const s16x4 lo = att::vtr(vp), hh = att::vtr(vp + 512);
;                 const bf16x8 vf = (bf16x8){lo[0], lo[1], lo[2], lo[3], hh[0], hh[1], hh[2], hh[3]}; acc[j] = ATT_MFMA(af, vf, acc[j]); }
;         }
;         int hi_e = hi, r32_e = r32; asm volatile("" : "+v"(hi_e), "+v"(r32_e));
;         const float* sbp = sb + g * 128 + 32 * tb + 4 * hi_e; bf16_t* hp = HC + (R0 + 32 * tb + 4 * hi_e) * 2048 + g * 128 + 64 * ch + r32_e;
;         bf16_t uu[16][2]; float bsv[16];
; #pragma unroll
;         for (int r = 0; r < 16; ++r) { bsv[r] = sbp[att::crow(r, 0)];
; #pragma unroll
;             for (int j = 0; j < 2; ++j) uu[r][j] = hp[att::crow(r, 0) * 2048 + 32 * j]; }
;         asm volatile("" ::: "memory");
; #pragma unroll
;         for (int r = 0; r < 16; ++r)
; #pragma unroll
;             for (int j = 0; j < 2; ++j) { const float u = __uint_as_float((unsigned)uu[r][j] << 16);
;                 hp[att::crow(r, 0) * 2048 + 32 * j] = (bf16_t)(cvt_pk_bf16(u * (acc[j][r] + bsv[r]), 0.f) & 0xffffu); }
;         __syncthreads();
	v_mfma_f32_32x32x16_bf16 v[0:15], v[232:235], v[36:39], v[0:15]
	ds_read_b64_tr_b16 v[36:37], v76 offset:6144
	ds_read_b64_tr_b16 v[38:39], v76 offset:6656
	s_waitcnt lgkmcnt(0)
	v_mfma_f32_32x32x16_bf16 v[16:31], v[236:239], v[36:39], v[16:31]
	ds_read_b64_tr_b16 v[36:37], v76 offset:14336
	ds_read_b64_tr_b16 v[38:39], v76 offset:14848
	s_waitcnt lgkmcnt(0)
	v_mfma_f32_32x32x16_bf16 v[0:15], v[236:239], v[36:39], v[0:15]
	ds_read_b64_tr_b16 v[36:37], v76 offset:7168
	ds_read_b64_tr_b16 v[38:39], v76 offset:7680
	s_waitcnt lgkmcnt(0)
	v_mfma_f32_32x32x16_bf16 v[16:31], v[240:243], v[36:39], v[16:31]
	ds_read_b64_tr_b16 v[36:37], v76 offset:15360
	ds_read_b64_tr_b16 v[38:39], v76 offset:15872
	s_waitcnt lgkmcnt(0)
	v_mfma_f32_32x32x16_bf16 v[0:15], v[240:243], v[36:39], v[0:15]
	ds_read_b64_tr_b16 v[36:37], v76 offset:8192
	ds_read_b64_tr_b16 v[38:39], v76 offset:8704
	s_waitcnt lgkmcnt(0)
	v_mfma_f32_32x32x16_bf16 v[16:31], v[244:247], v[36:39], v[16:31]
	ds_read_b64_tr_b16 v[36:37], v76 offset:16384
	ds_read_b64_tr_b16 v[38:39], v76 offset:16896
	s_waitcnt lgkmcnt(0)
	v_mfma_f32_32x32x16_bf16 v[0:15], v[244:247], v[36:39], v[0:15]
	v_lshrrev_b32_e32 v94, 6, v231
	v_mul_u32_u24_e32 v94, 0x2200, v94
	v_add_u32_e32 v94, 0x9000, v94
	v_mul_u32_u24_e32 v95, 0x440, v67
	v_lshl_add_u32 v95, v66, 2, v95
	v_lshrrev_b32_e32 v90, 1, v230
	v_mul_u32_u24_e32 v90, 0x110, v90
	v_and_b32_e32 v91, 1, v230
	v_lshl_add_u32 v90, v91, 7, v90
	v_add_u32_e32 v95, v94, v95
	v_add_u32_e32 v94, v94, v90
	s_waitcnt vmcnt(4)
	v_add_f32_e32 v16, v16, v78
	v_add_f32_e32 v0, v0, v78
	v_add_f32_e32 v17, v17, v79
	v_add_f32_e32 v1, v1, v79
	v_add_f32_e32 v18, v18, v80
	v_add_f32_e32 v2, v2, v80
	v_add_f32_e32 v19, v19, v81
	v_add_f32_e32 v3, v3, v81
	v_add_f32_e32 v20, v20, v82
	v_add_f32_e32 v4, v4, v82
	v_add_f32_e32 v21, v21, v83
	v_add_f32_e32 v5, v5, v83
	v_add_f32_e32 v22, v22, v84
	v_add_f32_e32 v6, v6, v84
	v_add_f32_e32 v23, v23, v85
	v_add_f32_e32 v7, v7, v85
	v_add_f32_e32 v24, v24, v164
	v_add_f32_e32 v8, v8, v164
	v_add_f32_e32 v25, v25, v165
	v_add_f32_e32 v9, v9, v165
	v_add_f32_e32 v26, v26, v166
	v_add_f32_e32 v10, v10, v166
	v_add_f32_e32 v27, v27, v167
	v_add_f32_e32 v11, v11, v167
	v_add_f32_e32 v28, v28, v32
	v_add_f32_e32 v12, v12, v32
	v_add_f32_e32 v29, v29, v33
	v_add_f32_e32 v13, v13, v33
	v_add_f32_e32 v30, v30, v34
	v_add_f32_e32 v14, v14, v34
	v_add_f32_e32 v31, v31, v35
	v_add_f32_e32 v15, v15, v35
	ds_write_b32 v95, v16
	ds_write_b32 v95, v0 offset:128
	ds_write_b32 v95, v17 offset:272
	ds_write_b32 v95, v1 offset:400
	ds_write_b32 v95, v18 offset:544
	ds_write_b32 v95, v2 offset:672
	ds_write_b32 v95, v19 offset:816
	ds_write_b32 v95, v3 offset:944
	ds_write_b32 v95, v20 offset:2176
	ds_write_b32 v95, v4 offset:2304
	ds_write_b32 v95, v21 offset:2448
	ds_write_b32 v95, v5 offset:2576
	ds_write_b32 v95, v22 offset:2720
	ds_write_b32 v95, v6 offset:2848
	ds_write_b32 v95, v23 offset:2992
	ds_write_b32 v95, v7 offset:3120
	ds_write_b32 v95, v24 offset:4352
	ds_write_b32 v95, v8 offset:4480
	ds_write_b32 v95, v25 offset:4624
	ds_write_b32 v95, v9 offset:4752
	ds_write_b32 v95, v26 offset:4896
	ds_write_b32 v95, v10 offset:5024
	ds_write_b32 v95, v27 offset:5168
	ds_write_b32 v95, v11 offset:5296
	ds_write_b32 v95, v28 offset:6528
	ds_write_b32 v95, v12 offset:6656
	ds_write_b32 v95, v29 offset:6800
	ds_write_b32 v95, v13 offset:6928
	ds_write_b32 v95, v30 offset:7072
	ds_write_b32 v95, v14 offset:7200
	ds_write_b32 v95, v31 offset:7344
	ds_write_b32 v95, v15 offset:7472
	s_waitcnt lgkmcnt(0)
	ds_read_b128 v[96:99], v94
	ds_read_b128 v[100:103], v94 offset:16
	ds_read_b128 v[104:107], v94 offset:32
	ds_read_b128 v[108:111], v94 offset:48
	ds_read_b128 v[112:115], v94 offset:64
	ds_read_b128 v[116:119], v94 offset:80
	ds_read_b128 v[120:123], v94 offset:96
	ds_read_b128 v[124:127], v94 offset:112
	s_waitcnt vmcnt(0) lgkmcnt(0)
	v_lshlrev_b32_e32 v144, 16, v128
	v_and_b32_e32 v145, 0xffff0000, v128
	v_mul_f32_e32 v144, v144, v96
	v_mul_f32_e32 v145, v145, v97
	v_cvt_pk_bf16_f32 v128, v144, v145
	v_lshlrev_b32_e32 v146, 16, v129
	v_and_b32_e32 v147, 0xffff0000, v129
	v_mul_f32_e32 v146, v146, v98
	v_mul_f32_e32 v147, v147, v99
	v_cvt_pk_bf16_f32 v129, v146, v147
	v_lshlrev_b32_e32 v144, 16, v130
	v_and_b32_e32 v145, 0xffff0000, v130
	v_mul_f32_e32 v144, v144, v100
	v_mul_f32_e32 v145, v145, v101
	v_cvt_pk_bf16_f32 v130, v144, v145
	v_lshlrev_b32_e32 v146, 16, v131
	v_and_b32_e32 v147, 0xffff0000, v131
	v_mul_f32_e32 v146, v146, v102
	v_mul_f32_e32 v147, v147, v103
	v_cvt_pk_bf16_f32 v131, v146, v147
	v_lshlrev_b32_e32 v144, 16, v132
	v_and_b32_e32 v145, 0xffff0000, v132
	v_mul_f32_e32 v144, v144, v104
	v_mul_f32_e32 v145, v145, v105
	v_cvt_pk_bf16_f32 v132, v144, v145
	v_lshlrev_b32_e32 v146, 16, v133
	v_and_b32_e32 v147, 0xffff0000, v133
	v_mul_f32_e32 v146, v146, v106
	v_mul_f32_e32 v147, v147, v107
	v_cvt_pk_bf16_f32 v133, v146, v147
	v_lshlrev_b32_e32 v144, 16, v134
	v_and_b32_e32 v145, 0xffff0000, v134
	v_mul_f32_e32 v144, v144, v108
	v_mul_f32_e32 v145, v145, v109
	v_cvt_pk_bf16_f32 v134, v144, v145
	v_lshlrev_b32_e32 v146, 16, v135
	v_and_b32_e32 v147, 0xffff0000, v135
	v_mul_f32_e32 v146, v146, v110
	v_mul_f32_e32 v147, v147, v111
	v_cvt_pk_bf16_f32 v135, v146, v147
	v_lshlrev_b32_e32 v144, 16, v136
	v_and_b32_e32 v145, 0xffff0000, v136
	v_mul_f32_e32 v144, v144, v112
	v_mul_f32_e32 v145, v145, v113
	v_cvt_pk_bf16_f32 v136, v144, v145
	v_lshlrev_b32_e32 v146, 16, v137
	v_and_b32_e32 v147, 0xffff0000, v137
	v_mul_f32_e32 v146, v146, v114
	v_mul_f32_e32 v147, v147, v115
	v_cvt_pk_bf16_f32 v137, v146, v147
	v_lshlrev_b32_e32 v144, 16, v138
	v_and_b32_e32 v145, 0xffff0000, v138
	v_mul_f32_e32 v144, v144, v116
	v_mul_f32_e32 v145, v145, v117
	v_cvt_pk_bf16_f32 v138, v144, v145
	v_lshlrev_b32_e32 v146, 16, v139
	v_and_b32_e32 v147, 0xffff0000, v139
	v_mul_f32_e32 v146, v146, v118
	v_mul_f32_e32 v147, v147, v119
	v_cvt_pk_bf16_f32 v139, v146, v147
	v_lshlrev_b32_e32 v144, 16, v140
	v_and_b32_e32 v145, 0xffff0000, v140
	v_mul_f32_e32 v144, v144, v120
	v_mul_f32_e32 v145, v145, v121
	v_cvt_pk_bf16_f32 v140, v144, v145
	v_lshlrev_b32_e32 v146, 16, v141
	v_and_b32_e32 v147, 0xffff0000, v141
	v_mul_f32_e32 v146, v146, v122
	v_mul_f32_e32 v147, v147, v123
	v_cvt_pk_bf16_f32 v141, v146, v147
	v_lshlrev_b32_e32 v144, 16, v142
	v_and_b32_e32 v145, 0xffff0000, v142
	v_mul_f32_e32 v144, v144, v124
	v_mul_f32_e32 v145, v145, v125
	v_cvt_pk_bf16_f32 v142, v144, v145
	v_lshlrev_b32_e32 v146, 16, v143
	v_and_b32_e32 v147, 0xffff0000, v143
	v_mul_f32_e32 v146, v146, v126
	v_mul_f32_e32 v147, v147, v127
	v_cvt_pk_bf16_f32 v143, v146, v147
	global_store_dwordx4 v[92:93], v[128:131], off
	global_store_dwordx4 v[92:93], v[132:135], off offset:16
	global_store_dwordx4 v[92:93], v[136:139], off offset:32
	global_store_dwordx4 v[92:93], v[140:143], off offset:48
	s_add_u32 s44, s44, 0x200
	s_addc_u32 s45, s45, 0
	s_add_u32 s46, s46, 0x100
	s_addc_u32 s47, s47, 0
	s_cmpk_lg_i32 s44, 0x1000
	s_barrier
; __device__ __forceinline__ void sgu_chunk(const Ctx& C, const Args& a, int l, int n) {
;     ...
;     for (int g = 0; g < 8; ++g) {
; __global__ void __launch_bounds__(512, 2) mk_fwd(Args a) {
;     ...
;                 for (int n = bx; n < 256; n += G) sgu_chunk(C, a, l, n);
	s_cbranch_scc1 .LBB0_154
	s_add_i32 s29, s29, s88
	v_readlane_b32 s0, v249, 56
	v_readlane_b32 s12, v249, 50
	v_readlane_b32 s1, v249, 57
	s_add_u32 s40, s40, s0
	v_readlane_b32 s13, v249, 51
	s_addc_u32 s41, s41, s1
	s_cmpk_gt_i32 s29, 0xff
	v_lshl_add_u64 v[40:41], v[40:41], 0, s[12:13]
	v_lshl_add_u64 v[42:43], v[42:43], 0, s[12:13]
	v_lshl_add_u64 v[44:45], v[44:45], 0, s[12:13]
	v_lshl_add_u64 v[46:47], v[46:47], 0, s[12:13]
	v_lshl_add_u64 v[48:49], v[48:49], 0, s[12:13]
	s_cbranch_scc0 .LBB0_149
